# POST LSE-merge loop: the three partial-output loads issued together with the LSE loads (renamed registers), one exposed memory latency per iteration instead of two
# baseline (speedup 1.0000x reference)
.LBB0_758:
	v_ashrrev_i32_e32 v14, 6, v13
	v_ashrrev_i32_e32 v15, 31, v14
	v_lshlrev_b64 v[16:17], 5, v[14:15]
	v_lshl_add_u64 v[16:17], v[2:3], 0, v[16:17]
	v_lshl_add_u64 v[18:19], v[14:15], 0, s[48:49]
	global_load_dword v20, v[16:17], off
	v_lshlrev_b64 v[16:17], 5, v[18:19]
	v_lshl_add_u64 v[16:17], v[2:3], 0, v[16:17]
	v_lshl_add_u64 v[22:23], v[14:15], 0, s[46:47]
	global_load_dword v21, v[16:17], off
	v_lshlrev_b64 v[16:17], 5, v[22:23]
	v_lshl_add_u64 v[16:17], v[2:3], 0, v[16:17]
	global_load_dword v16, v[16:17], off
	v_lshlrev_b64 v[32:33], 10, v[14:15]
	v_lshlrev_b64 v[18:19], 10, v[18:19]
	v_lshl_add_u64 v[14:15], v[8:9], 0, v[32:33]
	v_lshl_add_u64 v[18:19], v[8:9], 0, v[18:19]
	v_lshlrev_b64 v[22:23], 10, v[22:23]
	v_lshl_add_u64 v[22:23], v[8:9], 0, v[22:23]
	v_add_u32_e32 v13, s76, v13
	global_load_dwordx4 v[46:49], v[14:15], off nt
	global_load_dwordx4 v[50:53], v[18:19], off nt
	global_load_dwordx4 v[54:57], v[22:23], off nt
	s_waitcnt vmcnt(3)
	v_max3_f32 v17, v20, v21, v16
	v_sub_f32_e32 v20, v20, v17
	v_exp_f32_e32 v27, v20
	v_sub_f32_e32 v20, v21, v17
	v_exp_f32_e32 v26, v20
	v_sub_f32_e32 v16, v16, v17
	v_exp_f32_e32 v16, v16
	v_add_f32_e32 v17, v27, v26
	v_add_f32_e32 v17, v16, v17
	s_nop 0
	s_nop 0
	s_mov_b32 s4, 0xfffff
	s_nop 0
	s_nop 0
	s_nop 0
	s_nop 0
	s_nop 0
	s_nop 0
	s_nop 0
	s_nop 0
	v_rcp_f32_e32 v28, v17
	s_nop 0
	v_mul_f32_e32 v30, v16, v28
	v_pk_mul_f32 v[26:27], v[26:27], v[28:29] op_sel_hi:[1,0]
	v_cmp_lt_i32_e32 vcc, s4, v13
	s_or_b64 s[2:3], vcc, s[2:3]
	s_waitcnt vmcnt(2)
	v_lshlrev_b32_e32 v34, 16, v46
	v_and_b32_e32 v29, 0xffff0000, v46
	s_waitcnt vmcnt(1)
	v_and_b32_e32 v35, 0xffff0000, v50
	v_lshlrev_b32_e32 v28, 16, v50
	v_pk_mul_f32 v[34:35], v[26:27], v[34:35] op_sel:[1,0] op_sel_hi:[0,1]
	s_waitcnt vmcnt(0)
	v_lshlrev_b32_e32 v36, 16, v54
	v_and_b32_e32 v37, 0xffff0000, v54
	v_pk_fma_f32 v[28:29], v[26:27], v[28:29], v[34:35]
	v_lshlrev_b32_e32 v50, 16, v47
	v_pk_fma_f32 v[28:29], v[30:31], v[36:37], v[28:29] op_sel_hi:[0,1,1]
	v_cvt_pk_bf16_f32 v46, v28, v29
	v_lshlrev_b32_e32 v28, 16, v51
	v_and_b32_e32 v51, 0xffff0000, v51
	v_and_b32_e32 v29, 0xffff0000, v47
	v_pk_mul_f32 v[50:51], v[26:27], v[50:51] op_sel:[1,0] op_sel_hi:[0,1]
	v_lshlrev_b32_e32 v54, 16, v55
	v_and_b32_e32 v55, 0xffff0000, v55
	v_pk_fma_f32 v[50:51], v[26:27], v[28:29], v[50:51]
	v_lshlrev_b32_e32 v28, 16, v56
	v_pk_fma_f32 v[50:51], v[30:31], v[54:55], v[50:51] op_sel_hi:[0,1,1]
	v_lshlrev_b32_e32 v54, 16, v48
	v_and_b32_e32 v55, 0xffff0000, v52
	v_cvt_pk_bf16_f32 v47, v50, v51
	v_lshlrev_b32_e32 v50, 16, v52
	v_and_b32_e32 v51, 0xffff0000, v48
	v_pk_mul_f32 v[54:55], v[26:27], v[54:55] op_sel:[1,0] op_sel_hi:[0,1]
	v_and_b32_e32 v29, 0xffff0000, v56
	v_pk_fma_f32 v[50:51], v[26:27], v[50:51], v[54:55]
	v_lshlrev_b32_e32 v52, 16, v49
	v_pk_fma_f32 v[50:51], v[30:31], v[28:29], v[50:51] op_sel_hi:[0,1,1]
	v_cvt_pk_bf16_f32 v48, v50, v51
	v_lshlrev_b32_e32 v50, 16, v53
	v_and_b32_e32 v53, 0xffff0000, v53
	v_and_b32_e32 v51, 0xffff0000, v49
	v_pk_mul_f32 v[52:53], v[26:27], v[52:53] op_sel:[1,0] op_sel_hi:[0,1]
	v_pk_fma_f32 v[50:51], v[26:27], v[50:51], v[52:53]
	v_lshlrev_b32_e32 v52, 16, v57
	v_and_b32_e32 v53, 0xffff0000, v57
	v_pk_fma_f32 v[50:51], v[30:31], v[52:53], v[50:51] op_sel_hi:[0,1,1]
	v_cvt_pk_bf16_f32 v49, v50, v51
	v_lshl_add_u64 v[50:51], v[10:11], 0, v[32:33]
	global_store_dwordx4 v[50:51], v[46:49], off nt
	s_andn2_b64 exec, exec, s[2:3]
	s_cbranch_execnz .LBB0_758
